# attention tile loop: one static priority raise for the younger half-workgroup (waves 4..7) for the whole unit; GEMM loops without priority toggles
# speedup vs baseline: 1.0036x; 1.0036x over previous
.Lat_entry:
	s_cmp_lg_u64 s[0:1], 0
	s_cbranch_scc1 .Lat_prio_done
	s_setprio 1

.Lat_end_b:
.Lat_done:
	s_waitcnt vmcnt(0) lgkmcnt(0)
	v_lshl_add_u32 v250, v211, 4, s97
	ds_read_b128 v[130:133], v250
	ds_read_b128 v[134:137], v250 offset:1024
	ds_read_b128 v[138:141], v250 offset:2048
	ds_read_b128 v[142:145], v250 offset:3072
	ds_read_b128 v[146:149], v250 offset:4096
	ds_read_b128 v[150:153], v250 offset:5120
	ds_read_b128 v[154:157], v250 offset:6144
	ds_read_b128 v[158:161], v250 offset:7168
	s_waitcnt lgkmcnt(0)
	s_barrier
	s_setprio 0
	s_mov_b32 m0, s92
	s_nop 1
	v_permlane16_swap_b32_e32 v232, v244
	v_add_f32_e32 v232, v232, v244
	v_mov_b32_e32 v244, v232
	s_nop 1
	v_permlane32_swap_b32_e32 v232, v244
	v_add_f32_e32 v232, v232, v244
	v_mov_b32_e32 v244, v232
	s_nop 1
	v_permlane16_swap_b32_e32 v232, v244
	s_nop 0
	v_div_scale_f32 v162, s[6:7], v232, v232, 1.0
	v_rcp_f32_e32 v163, v162
	v_div_scale_f32 v164, vcc, 1.0, v232, 1.0
	v_fma_f32 v165, -v162, v163, 1.0
	v_fmac_f32_e32 v163, v165, v163
	v_mul_f32_e32 v165, v164, v163
	v_fma_f32 v166, -v162, v165, v164
	v_fmac_f32_e32 v165, v166, v163
	v_fma_f32 v162, -v162, v165, v164
	v_div_fmas_f32 v162, v162, v163, v165
	v_div_fixup_f32 v232, v162, v232, 1.0
	v_div_scale_f32 v167, s[6:7], v244, v244, 1.0
	v_rcp_f32_e32 v168, v167
	v_div_scale_f32 v169, vcc, 1.0, v244, 1.0
	v_fma_f32 v170, -v167, v168, 1.0
	v_fmac_f32_e32 v168, v170, v168
	v_mul_f32_e32 v170, v169, v168
	v_fma_f32 v171, -v167, v170, v169
	v_fmac_f32_e32 v170, v171, v168
	v_fma_f32 v167, -v167, v170, v169
	v_div_fmas_f32 v167, v167, v168, v170
	v_div_fixup_f32 v244, v167, v244, 1.0
	s_lshl_b64 s[4:5], s[82:83], 1
	v_mul_f32_e32 v114, v114, v232
	v_mul_f32_e32 v115, v115, v232
	v_mul_f32_e32 v116, v116, v232
	v_mul_f32_e32 v117, v117, v232
	v_mul_f32_e32 v118, v118, v232
	v_mul_f32_e32 v119, v119, v232
	v_mul_f32_e32 v120, v120, v232
	v_mul_f32_e32 v121, v121, v232
	v_mul_f32_e32 v98, v98, v232
	v_mul_f32_e32 v99, v99, v232
	v_mul_f32_e32 v100, v100, v232
	v_mul_f32_e32 v101, v101, v232
	v_mul_f32_e32 v102, v102, v232
	v_mul_f32_e32 v103, v103, v232
	v_mul_f32_e32 v104, v104, v232
	v_mul_f32_e32 v105, v105, v232
	v_mul_f32_e32 v82, v82, v232
	v_mul_f32_e32 v83, v83, v232
	v_mul_f32_e32 v84, v84, v232
	v_mul_f32_e32 v85, v85, v232
	v_mul_f32_e32 v86, v86, v232
	v_mul_f32_e32 v87, v87, v232
	v_mul_f32_e32 v88, v88, v232
	v_mul_f32_e32 v89, v89, v232
	v_mul_f32_e32 v66, v66, v232
	v_mul_f32_e32 v67, v67, v232
	v_mul_f32_e32 v68, v68, v232
	v_mul_f32_e32 v69, v69, v232
	v_mul_f32_e32 v70, v70, v232
	v_mul_f32_e32 v71, v71, v232
	v_mul_f32_e32 v72, v72, v232
	v_mul_f32_e32 v73, v73, v232
	v_mul_f32_e32 v50, v50, v232
	v_mul_f32_e32 v51, v51, v232
	v_mul_f32_e32 v52, v52, v232
	v_mul_f32_e32 v53, v53, v232
	v_mul_f32_e32 v54, v54, v232
	v_mul_f32_e32 v55, v55, v232
	v_mul_f32_e32 v56, v56, v232
	v_mul_f32_e32 v57, v57, v232
	v_mul_f32_e32 v34, v34, v232
	v_mul_f32_e32 v35, v35, v232
	v_mul_f32_e32 v36, v36, v232
	v_mul_f32_e32 v37, v37, v232
	v_mul_f32_e32 v38, v38, v232
	v_mul_f32_e32 v39, v39, v232
	v_mul_f32_e32 v40, v40, v232
	v_mul_f32_e32 v41, v41, v232
	v_mul_f32_e32 v18, v18, v232
	v_mul_f32_e32 v19, v19, v232
	v_mul_f32_e32 v20, v20, v232
	v_mul_f32_e32 v21, v21, v232
	v_mul_f32_e32 v22, v22, v232
	v_mul_f32_e32 v23, v23, v232
	v_mul_f32_e32 v24, v24, v232
	v_mul_f32_e32 v25, v25, v232
	v_mul_f32_e32 v2, v2, v232
	v_mul_f32_e32 v3, v3, v232
	v_mul_f32_e32 v4, v4, v232
	v_mul_f32_e32 v5, v5, v232
	v_mul_f32_e32 v6, v6, v232
	v_mul_f32_e32 v7, v7, v232
	v_mul_f32_e32 v8, v8, v232
	v_mul_f32_e32 v9, v9, v232
	v_mul_f32_e32 v122, v122, v244
	v_mul_f32_e32 v123, v123, v244
	v_mul_f32_e32 v124, v124, v244
	v_mul_f32_e32 v125, v125, v244
	v_mul_f32_e32 v126, v126, v244
	v_mul_f32_e32 v127, v127, v244
	v_mul_f32_e32 v128, v128, v244
	v_mul_f32_e32 v129, v129, v244
	v_mul_f32_e32 v106, v106, v244
	v_mul_f32_e32 v107, v107, v244
	v_mul_f32_e32 v108, v108, v244
	v_mul_f32_e32 v109, v109, v244
	v_mul_f32_e32 v110, v110, v244
	v_mul_f32_e32 v111, v111, v244
	v_mul_f32_e32 v112, v112, v244
	v_mul_f32_e32 v113, v113, v244
	v_mul_f32_e32 v90, v90, v244
	v_mul_f32_e32 v91, v91, v244
	v_mul_f32_e32 v92, v92, v244
	v_mul_f32_e32 v93, v93, v244
	v_mul_f32_e32 v94, v94, v244
	v_mul_f32_e32 v95, v95, v244
	v_mul_f32_e32 v96, v96, v244
	v_mul_f32_e32 v97, v97, v244
	v_mul_f32_e32 v74, v74, v244
	v_mul_f32_e32 v75, v75, v244
	v_mul_f32_e32 v76, v76, v244
	v_mul_f32_e32 v77, v77, v244
	v_mul_f32_e32 v78, v78, v244
	v_mul_f32_e32 v79, v79, v244
	v_mul_f32_e32 v80, v80, v244
	v_mul_f32_e32 v81, v81, v244
	v_mul_f32_e32 v58, v58, v244
	v_mul_f32_e32 v59, v59, v244
	v_mul_f32_e32 v60, v60, v244
	v_mul_f32_e32 v61, v61, v244
	v_mul_f32_e32 v62, v62, v244
	v_mul_f32_e32 v63, v63, v244
	v_mul_f32_e32 v64, v64, v244
	v_mul_f32_e32 v65, v65, v244
	v_mul_f32_e32 v42, v42, v244
	v_mul_f32_e32 v43, v43, v244
	v_mul_f32_e32 v44, v44, v244
	v_mul_f32_e32 v45, v45, v244
	v_mul_f32_e32 v46, v46, v244
	v_mul_f32_e32 v47, v47, v244
	v_mul_f32_e32 v48, v48, v244
	v_mul_f32_e32 v49, v49, v244
	v_mul_f32_e32 v26, v26, v244
	v_mul_f32_e32 v27, v27, v244
	v_mul_f32_e32 v28, v28, v244
	v_mul_f32_e32 v29, v29, v244
	v_mul_f32_e32 v30, v30, v244
	v_mul_f32_e32 v31, v31, v244
	v_mul_f32_e32 v32, v32, v244
	v_mul_f32_e32 v33, v33, v244
	v_mul_f32_e32 v10, v10, v244
	v_mul_f32_e32 v11, v11, v244
	v_mul_f32_e32 v12, v12, v244
	v_mul_f32_e32 v13, v13, v244
	v_mul_f32_e32 v14, v14, v244
	v_mul_f32_e32 v15, v15, v244
	v_mul_f32_e32 v16, v16, v244
	v_mul_f32_e32 v17, v17, v244
	s_cmp_lg_u64 s[0:1], 0
	s_cbranch_scc1 .Lat_ep_k
	v_mul_f32_e32 v114, v114, v210
	v_mul_f32_e32 v115, v115, v210
	v_mul_f32_e32 v116, v116, v210
	v_mul_f32_e32 v117, v117, v210
	v_mul_f32_e32 v118, v118, v210
	v_mul_f32_e32 v119, v119, v210
	v_mul_f32_e32 v120, v120, v210
	v_mul_f32_e32 v121, v121, v210
	v_mul_f32_e32 v98, v98, v210
	v_mul_f32_e32 v99, v99, v210
	v_mul_f32_e32 v100, v100, v210
	v_mul_f32_e32 v101, v101, v210
	v_mul_f32_e32 v102, v102, v210
	v_mul_f32_e32 v103, v103, v210
	v_mul_f32_e32 v104, v104, v210
	v_mul_f32_e32 v105, v105, v210
	v_mul_f32_e32 v82, v82, v210
	v_mul_f32_e32 v83, v83, v210
	v_mul_f32_e32 v84, v84, v210
	v_mul_f32_e32 v85, v85, v210
	v_mul_f32_e32 v86, v86, v210
	v_mul_f32_e32 v87, v87, v210
	v_mul_f32_e32 v88, v88, v210
	v_mul_f32_e32 v89, v89, v210
	v_mul_f32_e32 v66, v66, v210
	v_mul_f32_e32 v67, v67, v210
	v_mul_f32_e32 v68, v68, v210
	v_mul_f32_e32 v69, v69, v210
	v_mul_f32_e32 v70, v70, v210
	v_mul_f32_e32 v71, v71, v210
	v_mul_f32_e32 v72, v72, v210
	v_mul_f32_e32 v73, v73, v210
	v_mul_f32_e32 v50, v50, v210
	v_mul_f32_e32 v51, v51, v210
	v_mul_f32_e32 v52, v52, v210
	v_mul_f32_e32 v53, v53, v210
	v_mul_f32_e32 v54, v54, v210
	v_mul_f32_e32 v55, v55, v210
	v_mul_f32_e32 v56, v56, v210
	v_mul_f32_e32 v57, v57, v210
	v_mul_f32_e32 v34, v34, v210
	v_mul_f32_e32 v35, v35, v210
	v_mul_f32_e32 v36, v36, v210
	v_mul_f32_e32 v37, v37, v210
	v_mul_f32_e32 v38, v38, v210
	v_mul_f32_e32 v39, v39, v210
	v_mul_f32_e32 v40, v40, v210
	v_mul_f32_e32 v41, v41, v210
	v_mul_f32_e32 v18, v18, v210
	v_mul_f32_e32 v19, v19, v210
	v_mul_f32_e32 v20, v20, v210
	v_mul_f32_e32 v21, v21, v210
	v_mul_f32_e32 v22, v22, v210
	v_mul_f32_e32 v23, v23, v210
	v_mul_f32_e32 v24, v24, v210
	v_mul_f32_e32 v25, v25, v210
	v_mul_f32_e32 v2, v2, v210
	v_mul_f32_e32 v3, v3, v210
	v_mul_f32_e32 v4, v4, v210
	v_mul_f32_e32 v5, v5, v210
	v_mul_f32_e32 v6, v6, v210
	v_mul_f32_e32 v7, v7, v210
	v_mul_f32_e32 v8, v8, v210
	v_mul_f32_e32 v9, v9, v210
	v_mul_f32_e32 v122, v122, v210
	v_mul_f32_e32 v123, v123, v210
	v_mul_f32_e32 v124, v124, v210
	v_mul_f32_e32 v125, v125, v210
	v_mul_f32_e32 v126, v126, v210
	v_mul_f32_e32 v127, v127, v210
	v_mul_f32_e32 v128, v128, v210
	v_mul_f32_e32 v129, v129, v210
	v_mul_f32_e32 v106, v106, v210
	v_mul_f32_e32 v107, v107, v210
	v_mul_f32_e32 v108, v108, v210
	v_mul_f32_e32 v109, v109, v210
	v_mul_f32_e32 v110, v110, v210
	v_mul_f32_e32 v111, v111, v210
	v_mul_f32_e32 v112, v112, v210
	v_mul_f32_e32 v113, v113, v210
	v_mul_f32_e32 v90, v90, v210
	v_mul_f32_e32 v91, v91, v210
	v_mul_f32_e32 v92, v92, v210
	v_mul_f32_e32 v93, v93, v210
	v_mul_f32_e32 v94, v94, v210
	v_mul_f32_e32 v95, v95, v210
	v_mul_f32_e32 v96, v96, v210
	v_mul_f32_e32 v97, v97, v210
	v_mul_f32_e32 v74, v74, v210
	v_mul_f32_e32 v75, v75, v210
	v_mul_f32_e32 v76, v76, v210
	v_mul_f32_e32 v77, v77, v210
	v_mul_f32_e32 v78, v78, v210
	v_mul_f32_e32 v79, v79, v210
	v_mul_f32_e32 v80, v80, v210
	v_mul_f32_e32 v81, v81, v210
	v_mul_f32_e32 v58, v58, v210
	v_mul_f32_e32 v59, v59, v210
	v_mul_f32_e32 v60, v60, v210
	v_mul_f32_e32 v61, v61, v210
	v_mul_f32_e32 v62, v62, v210
	v_mul_f32_e32 v63, v63, v210
	v_mul_f32_e32 v64, v64, v210
	v_mul_f32_e32 v65, v65, v210
	v_mul_f32_e32 v42, v42, v210
	v_mul_f32_e32 v43, v43, v210
	v_mul_f32_e32 v44, v44, v210
	v_mul_f32_e32 v45, v45, v210
	v_mul_f32_e32 v46, v46, v210
	v_mul_f32_e32 v47, v47, v210
	v_mul_f32_e32 v48, v48, v210
	v_mul_f32_e32 v49, v49, v210
	v_mul_f32_e32 v26, v26, v210
	v_mul_f32_e32 v27, v27, v210
	v_mul_f32_e32 v28, v28, v210
	v_mul_f32_e32 v29, v29, v210
	v_mul_f32_e32 v30, v30, v210
	v_mul_f32_e32 v31, v31, v210
	v_mul_f32_e32 v32, v32, v210
	v_mul_f32_e32 v33, v33, v210
	v_mul_f32_e32 v10, v10, v210
	v_mul_f32_e32 v11, v11, v210
	v_mul_f32_e32 v12, v12, v210
	v_mul_f32_e32 v13, v13, v210
	v_mul_f32_e32 v14, v14, v210
	v_mul_f32_e32 v15, v15, v210
	v_mul_f32_e32 v16, v16, v210
	v_mul_f32_e32 v17, v17, v210
	v_lshl_add_u32 v250, v211, 4, s95
	ds_write_b128 v250, v[114:117]
	ds_write_b128 v250, v[118:121] offset:1024
	ds_write_b128 v250, v[98:101] offset:2048
	ds_write_b128 v250, v[102:105] offset:3072
	ds_write_b128 v250, v[82:85] offset:4096
	ds_write_b128 v250, v[86:89] offset:5120
	ds_write_b128 v250, v[66:69] offset:6144
	ds_write_b128 v250, v[70:73] offset:7168
	ds_write_b128 v250, v[50:53] offset:8192
	ds_write_b128 v250, v[54:57] offset:9216
	ds_write_b128 v250, v[34:37] offset:10240
	ds_write_b128 v250, v[38:41] offset:11264
	ds_write_b128 v250, v[18:21] offset:12288
	ds_write_b128 v250, v[22:25] offset:13312
	ds_write_b128 v250, v[2:5] offset:14336
	ds_write_b128 v250, v[6:9] offset:15360
	ds_write_b128 v250, v[122:125] offset:16384
	ds_write_b128 v250, v[126:129] offset:17408
	ds_write_b128 v250, v[106:109] offset:18432
	ds_write_b128 v250, v[110:113] offset:19456
	ds_write_b128 v250, v[90:93] offset:20480
	ds_write_b128 v250, v[94:97] offset:21504
	ds_write_b128 v250, v[74:77] offset:22528
	ds_write_b128 v250, v[78:81] offset:23552
	ds_write_b128 v250, v[58:61] offset:24576
	ds_write_b128 v250, v[62:65] offset:25600
	ds_write_b128 v250, v[42:45] offset:26624
	ds_write_b128 v250, v[46:49] offset:27648
	ds_write_b128 v250, v[26:29] offset:28672
	ds_write_b128 v250, v[30:33] offset:29696
	ds_write_b128 v250, v[10:13] offset:30720
	ds_write_b128 v250, v[14:17] offset:31744
	s_waitcnt lgkmcnt(0)
	s_barrier
	s_branch .Lat_ep_fin
